# software-pipelined weight conversion loops: next tile loads issued before current tile LDS transpose
# speedup vs baseline: 1.0065x; 1.0042x over previous
; DI unsigned cvt_pk_bf16(float lo, float hi) { unsigned r; asm volatile("v_cvt_pk_bf16_f32 %0, %1, %2" : "=v"(r) : "v"(lo), "v"(hi)); return r; }
; DI void convert_mat(LAS float* tile, const float* src, int K, int N, bf16_t* dst, int ffn_in_mode, int wave_s) {
;   const int tid = tid_fresh(wave_s), tk = K >> 6, tn = N >> 6;
;   for (int t = blockIdx.x; t < tk * tn; t += gridDim.x) {
;     const int kb = t % tk, nb = t / tk;
; #pragma unroll
;     for (int i = 0; i < 2; ++i) {
;       const int r = (tid >> 4) + 32 * i, c = (tid & 15) * 4;
;       const f32x4 v = *(const f32x4*)(src + (size_t)(kb * 64 + r) * N + nb * 64 + c);
;       tile[r * 65 + c] = v[0]; tile[r * 65 + c + 1] = v[1]; tile[r * 65 + c + 2] = v[2]; tile[r * 65 + c + 3] = v[3];
;     }
;     __syncthreads();
;     {
;       const int n = tid >> 3, k0 = (tid & 7) * 8;
;       float v[8];
; #pragma unroll
;       for (int j = 0; j < 8; ++j) v[j] = tile[(k0 + j) * 65 + n];
;       int no = nb * 64 + n;
;       if (ffn_in_mode) { const int half = no >= DFF ? 1 : 0; const int np = no - half * DFF; no = 256 * (np >> 7) + 128 * half + (np & 127); }
;       u32x4 w; w.x = cvt_pk_bf16(v[0], v[1]); w.y = cvt_pk_bf16(v[2], v[3]); w.z = cvt_pk_bf16(v[4], v[5]); w.w = cvt_pk_bf16(v[6], v[7]);
;       *(u32x4*)(dst + (size_t)no * K + kb * 64 + k0) = w;
.LBB0_351:
	s_mov_b32 s18, 0x6dc9c883
	s_andn2_b64 vcc, exec, s[64:65]
	s_mov_b32 s19, 0x3fc45f30
	s_movk_i32 s20, 0x1800
	s_movk_i32 s21, 0x6000
	s_mov_b32 s22, 0x8000
	s_movk_i32 s23, 0xaff
	s_movk_i32 s24, 0x7fff
	s_movk_i32 s25, 0x1600
	s_cbranch_vccnz .LBB0_625
	s_cmp_lg_u32 s68, 0
	s_cselect_b64 s[4:5], -1, 0
	s_cmp_eq_u32 s68, 0
	s_cselect_b64 s[0:1], -1, 0
	s_and_b64 s[6:7], s[0:1], exec
	v_readlane_b32 s6, v254, 44
	v_readlane_b32 s7, v254, 45
	s_cselect_b32 s2, 0, 2
	s_andn2_b64 vcc, exec, s[6:7]
	v_cndmask_b32_e64 v0, 0, 1, s[6:7]
	v_cmp_ne_u32_e64 s[8:9], 1, v0
	v_mbcnt_lo_u32_b32 v4, -1, 0
	v_mbcnt_hi_u32_b32 v4, -1, v4
	s_cbranch_vccnz .LBB0_355
	v_readlane_b32 s36, v255, 29
	s_mul_i32 s6, s2, 0x1600000
	v_readlane_b32 s42, v255, 35
	v_readlane_b32 s43, v255, 36
	s_add_u32 s6, s42, s6
	v_lshlrev_b32_e32 v0, 4, v4
	s_addc_u32 s7, s43, 0
	v_or_b32_e32 v3, s79, v4
	v_and_b32_e32 v176, 0xf0, v0
	v_lshlrev_b32_e32 v4, 3, v4
	v_ashrrev_i32_e32 v2, 4, v3
	v_lshl_add_u64 v[0:1], s[6:7], 0, v[176:177]
	v_ashrrev_i32_e32 v3, 3, v3
	v_and_b32_e32 v6, 56, v4
	s_movk_i32 s6, 0x104
	v_add_u32_e32 v5, 0, v176
	v_lshl_add_u32 v7, v3, 2, 0
	v_mul_lo_u32 v4, v2, s6
	s_waitcnt vmcnt(0)
	v_mul_u32_u24_e32 v8, 0x104, v6
	v_add_u32_e32 v4, v5, v4
	v_add_u32_e32 v5, v7, v8
	v_lshlrev_b32_e32 v176, 1, v6
	s_mov_b32 s6, s73
	v_readlane_b32 s37, v255, 30
	v_readlane_b32 s38, v255, 31
	v_readlane_b32 s39, v255, 32
	v_readlane_b32 s40, v255, 33
	v_readlane_b32 s41, v255, 34
	v_readlane_b32 s44, v255, 37
	v_readlane_b32 s45, v255, 38
	v_readlane_b32 s46, v255, 39
	v_readlane_b32 s47, v255, 40
	v_readlane_b32 s48, v255, 41
	v_readlane_b32 s49, v255, 42
	v_readlane_b32 s50, v255, 43
	v_readlane_b32 s51, v255, 44
	s_ashr_i32 s7, s6, 31
	s_lshr_b32 s7, s7, 28
	s_add_i32 s7, s6, s7
	s_and_b32 s10, s7, 0x3fffff0
	s_lshl_b32 s7, s7, 2
	s_sub_i32 s11, s6, s10
	s_and_b32 s10, s7, 0xffffffc0
	s_lshl_b32 s12, s11, 6
	s_ashr_i32 s11, s10, 31
	v_lshl_add_u64 v[34:35], s[10:11], 2, v[0:1]
	v_add_u32_e32 v32, s12, v2
	v_mad_i64_i32 v[30:31], s[14:15], v32, s81, v[34:35]
	v_add_u32_e32 v36, 32, v32
	global_load_dwordx4 v[30:33], v[30:31], off
	v_mad_i64_i32 v[34:35], s[14:15], v36, s81, v[34:35]
	global_load_dwordx4 v[34:37], v[34:35], off
.LBB0_354:
	s_waitcnt vmcnt(0)
	v_mov_b32_e32 v6, v30
	v_mov_b32_e32 v7, v31
	v_mov_b32_e32 v8, v32
	v_mov_b32_e32 v9, v33
	v_mov_b32_e32 v10, v34
	v_mov_b32_e32 v11, v35
	v_mov_b32_e32 v12, v36
	v_mov_b32_e32 v13, v37
	v_add_u32_e32 v14, s10, v3
	v_cmp_lt_i32_e32 vcc, s23, v14
	v_and_b32_e32 v19, 0x7f, v14
	v_add_u32_e32 v16, 0x2080, v4
	v_cndmask_b32_e32 v15, 0, v213, vcc
	v_add_lshl_u32 v14, v15, v14, 1
	v_cndmask_b32_e32 v15, 0, v214, vcc
	v_and_b32_e32 v14, 0xffffff00, v14
	v_or3_b32 v14, v15, v19, v14
	v_add_u32_e32 v17, 0x2088, v4
	v_add_u32_e32 v18, 0x400, v5
	v_ashrrev_i32_e32 v15, 31, v14
	v_lshlrev_b64 v[14:15], 11, v[14:15]
	s_ashr_i32 s13, s12, 31
	v_lshl_add_u64 v[14:15], s[86:87], 0, v[14:15]
	v_lshl_add_u64 v[14:15], s[12:13], 1, v[14:15]
	v_lshl_add_u64 v[14:15], v[14:15], 0, v[176:177]
	s_load_dword s7, s[88:89], 0x10
	s_load_dword s12, s[88:89], 0x0
	s_waitcnt lgkmcnt(0)
	s_lshr_b32 s7, s7, 16
	s_cmp_lg_u32 s7, 0
	s_cselect_b64 s[10:11], -1, 0
	s_cmp_lg_u64 s[10:11], 0
	s_addc_u32 s6, s12, s6
	s_cmpk_lt_i32 s6, 0x580
	s_cselect_b64 s[100:101], -1, 0
	s_cbranch_scc0 .Lcv_skip_354
	s_ashr_i32 s7, s6, 31
	s_lshr_b32 s7, s7, 28
	s_add_i32 s7, s6, s7
	s_and_b32 s10, s7, 0x3fffff0
	s_lshl_b32 s7, s7, 2
	s_sub_i32 s11, s6, s10
	s_and_b32 s10, s7, 0xffffffc0
	s_lshl_b32 s12, s11, 6
	s_ashr_i32 s11, s10, 31
	v_lshl_add_u64 v[34:35], s[10:11], 2, v[0:1]
	v_add_u32_e32 v32, s12, v2
	v_mad_i64_i32 v[30:31], s[14:15], v32, s81, v[34:35]
	v_add_u32_e32 v36, 32, v32
	global_load_dwordx4 v[30:33], v[30:31], off
	v_mad_i64_i32 v[34:35], s[14:15], v36, s81, v[34:35]
	global_load_dwordx4 v[34:37], v[34:35], off
; DI unsigned cvt_pk_bf16(float lo, float hi) { unsigned r; asm volatile("v_cvt_pk_bf16_f32 %0, %1, %2" : "=v"(r) : "v"(lo), "v"(hi)); return r; }
; DI void convert_mat(LAS float* tile, const float* src, int K, int N, bf16_t* dst, int ffn_in_mode, int wave_s) {
;     ...
;       tile[r * 65 + c] = v[0]; tile[r * 65 + c + 1] = v[1]; tile[r * 65 + c + 2] = v[2]; tile[r * 65 + c + 3] = v[3];
;     }
;     __syncthreads();
;     {
;       const int n = tid >> 3, k0 = (tid & 7) * 8;
;       float v[8];
; #pragma unroll
;       for (int j = 0; j < 8; ++j) v[j] = tile[(k0 + j) * 65 + n];
;       int no = nb * 64 + n;
;       if (ffn_in_mode) { const int half = no >= DFF ? 1 : 0; const int np = no - half * DFF; no = 256 * (np >> 7) + 128 * half + (np & 127); }
;       u32x4 w; w.x = cvt_pk_bf16(v[0], v[1]); w.y = cvt_pk_bf16(v[2], v[3]); w.z = cvt_pk_bf16(v[4], v[5]); w.w = cvt_pk_bf16(v[6], v[7]);
;       *(u32x4*)(dst + (size_t)no * K + kb * 64 + k0) = w;
;     }
;     __syncthreads();
; DI void convert_layer(LAS unsigned char* lds, const Params& p, int layer) {
;     ...
;     convert_mat(tile, p.ffn_out + (size_t)(layer * 2 + i) * DFF * DM, DFF, DM, (bf16_t*)(p.ws + OFF_FFN_OUT0 + i * SZ_FFN_OUT), 0, p.wave_s);
.Lcv_skip_354:
	ds_write2_b32 v4, v6, v7 offset1:1
	ds_write2_b32 v4, v8, v9 offset0:2 offset1:3
	ds_write2_b32 v16, v10, v11 offset1:1
	ds_write2_b32 v17, v12, v13 offset1:1
	s_waitcnt lgkmcnt(0)
	s_barrier
	ds_read2_b32 v[6:7], v5 offset1:65
	ds_read2_b32 v[8:9], v5 offset0:130 offset1:195
	ds_read2_b32 v[10:11], v18 offset0:4 offset1:69
	ds_read2_b32 v[12:13], v18 offset0:134 offset1:199
	s_waitcnt lgkmcnt(3)
	v_cvt_pk_bf16_f32 v6, v6, v7
	s_waitcnt lgkmcnt(2)
	v_cvt_pk_bf16_f32 v7, v8, v9
	s_waitcnt lgkmcnt(1)
	v_cvt_pk_bf16_f32 v8, v10, v11
	s_waitcnt lgkmcnt(0)
	v_cvt_pk_bf16_f32 v9, v12, v13
	global_store_dwordx4 v[14:15], v[6:9], off
	s_barrier
	s_and_b64 vcc, exec, s[100:101]
	s_cbranch_vccnz .LBB0_354
.LBB0_355:
	v_readlane_b32 s10, v254, 46
	v_readlane_b32 s11, v254, 47
	s_andn2_b64 vcc, exec, s[10:11]
	v_mbcnt_lo_u32_b32 v4, -1, 0
	v_mbcnt_hi_u32_b32 v4, -1, v4
	s_nop 0
	v_cndmask_b32_e64 v0, 0, 1, s[10:11]
	v_cmp_ne_u32_e64 s[6:7], 1, v0
	s_cbranch_vccnz .LBB0_358
	s_add_u32 s10, s86, 0x1600000
	v_readlane_b32 s36, v255, 29
	s_addc_u32 s11, s87, 0
	s_mul_i32 s12, s2, 0xb00000
	v_readlane_b32 s44, v255, 37
	v_readlane_b32 s45, v255, 38
	s_add_u32 s12, s44, s12
	v_lshlrev_b32_e32 v0, 4, v4
	s_addc_u32 s13, s45, 0
	v_or_b32_e32 v3, s79, v4
	v_and_b32_e32 v176, 0xf0, v0
	v_lshlrev_b32_e32 v4, 3, v4
	v_ashrrev_i32_e32 v2, 4, v3
	v_lshl_add_u64 v[0:1], s[12:13], 0, v[176:177]
	v_ashrrev_i32_e32 v3, 3, v3
	v_and_b32_e32 v6, 56, v4
	s_movk_i32 s12, 0x104
	v_add_u32_e32 v5, 0, v176
	v_lshl_add_u32 v7, v3, 2, 0
	v_mul_lo_u32 v4, v2, s12
	s_waitcnt vmcnt(0)
	v_mul_u32_u24_e32 v8, 0x104, v6
	v_add_u32_e32 v4, v5, v4
	v_add_u32_e32 v5, v7, v8
	v_lshlrev_b32_e32 v176, 1, v6
	s_mov_b32 s12, s73
	v_readlane_b32 s37, v255, 30
	v_readlane_b32 s38, v255, 31
	v_readlane_b32 s39, v255, 32
	v_readlane_b32 s40, v255, 33
	v_readlane_b32 s41, v255, 34
	v_readlane_b32 s42, v255, 35
	v_readlane_b32 s43, v255, 36
	v_readlane_b32 s46, v255, 39
	v_readlane_b32 s47, v255, 40
	v_readlane_b32 s48, v255, 41
	v_readlane_b32 s49, v255, 42
	v_readlane_b32 s50, v255, 43
	v_readlane_b32 s51, v255, 44
	s_mul_hi_i32 s13, s12, 0x2e8ba2e9
	s_lshr_b32 s14, s13, 31
	s_ashr_i32 s13, s13, 3
	s_add_i32 s13, s13, s14
	s_mul_i32 s15, s13, 44
	s_lshl_b32 s14, s13, 6
	s_sub_i32 s13, s12, s15
	s_lshl_b32 s16, s13, 6
	v_add_u32_e32 v30, s16, v2
	s_ashr_i32 s15, s14, 31
	v_ashrrev_i32_e32 v31, 31, v30
	v_lshl_add_u64 v[34:35], s[14:15], 2, v[0:1]
	v_add_u32_e32 v32, 32, v30
	v_lshlrev_b64 v[30:31], 12, v[30:31]
	v_ashrrev_i32_e32 v33, 31, v32
	v_lshl_add_u64 v[30:31], v[34:35], 0, v[30:31]
	v_lshlrev_b64 v[36:37], 12, v[32:33]
	global_load_dwordx4 v[30:33], v[30:31], off
	v_lshl_add_u64 v[34:35], v[34:35], 0, v[36:37]
	global_load_dwordx4 v[34:37], v[34:35], off
.LBB0_357:
	s_waitcnt vmcnt(0)
	v_mov_b32_e32 v6, v30
	v_mov_b32_e32 v7, v31
	v_mov_b32_e32 v8, v32
	v_mov_b32_e32 v9, v33
	v_mov_b32_e32 v10, v34
	v_mov_b32_e32 v11, v35
	v_mov_b32_e32 v12, v36
	v_mov_b32_e32 v13, v37
	v_add_u32_e32 v16, 0x2080, v4
	v_add_u32_e32 v17, 0x2088, v4
	v_add_u32_e32 v18, 0x400, v5
	v_mov_b64_e32 v[14:15], s[10:11]
	v_add_u32_e32 v19, s14, v3
	v_mad_i64_i32 v[14:15], s[14:15], v19, s25, v[14:15]
	s_ashr_i32 s17, s16, 31
	v_lshl_add_u64 v[14:15], s[16:17], 1, v[14:15]
	v_lshl_add_u64 v[14:15], v[14:15], 0, v[176:177]
	s_load_dword s13, s[88:89], 0x10
	s_load_dword s16, s[88:89], 0x0
	s_waitcnt lgkmcnt(0)
	s_lshr_b32 s13, s13, 16
	s_cmp_lg_u32 s13, 0
	s_cselect_b64 s[14:15], -1, 0
	s_cmp_lg_u64 s[14:15], 0
	s_addc_u32 s12, s16, s12
	s_cmpk_lt_i32 s12, 0x2c0
	s_cselect_b64 s[100:101], -1, 0
	s_cbranch_scc0 .Lcv_skip_357
	s_mul_hi_i32 s13, s12, 0x2e8ba2e9
	s_lshr_b32 s14, s13, 31
	s_ashr_i32 s13, s13, 3
	s_add_i32 s13, s13, s14
	s_mul_i32 s15, s13, 44
	s_lshl_b32 s14, s13, 6
	s_sub_i32 s13, s12, s15
	s_lshl_b32 s16, s13, 6
	v_add_u32_e32 v30, s16, v2
	s_ashr_i32 s15, s14, 31
	v_ashrrev_i32_e32 v31, 31, v30
	v_lshl_add_u64 v[34:35], s[14:15], 2, v[0:1]
	v_add_u32_e32 v32, 32, v30
	v_lshlrev_b64 v[30:31], 12, v[30:31]
	v_ashrrev_i32_e32 v33, 31, v32
	v_lshl_add_u64 v[30:31], v[34:35], 0, v[30:31]
	v_lshlrev_b64 v[36:37], 12, v[32:33]
	global_load_dwordx4 v[30:33], v[30:31], off
	v_lshl_add_u64 v[34:35], v[34:35], 0, v[36:37]
	global_load_dwordx4 v[34:37], v[34:35], off

; DI unsigned cvt_pk_bf16(float lo, float hi) { unsigned r; asm volatile("v_cvt_pk_bf16_f32 %0, %1, %2" : "=v"(r) : "v"(lo), "v"(hi)); return r; }
; DI void convert_mat(LAS float* tile, const float* src, int K, int N, bf16_t* dst, int ffn_in_mode, int wave_s) {
;   const int tid = tid_fresh(wave_s), tk = K >> 6, tn = N >> 6;
;   for (int t = blockIdx.x; t < tk * tn; t += gridDim.x) {
;     const int kb = t % tk, nb = t / tk;
; #pragma unroll
;     for (int i = 0; i < 2; ++i) {
;       const int r = (tid >> 4) + 32 * i, c = (tid & 15) * 4;
;       const f32x4 v = *(const f32x4*)(src + (size_t)(kb * 64 + r) * N + nb * 64 + c);
;       tile[r * 65 + c] = v[0]; tile[r * 65 + c + 1] = v[1]; tile[r * 65 + c + 2] = v[2]; tile[r * 65 + c + 3] = v[3];
;     }
;     __syncthreads();
;     {
;       const int n = tid >> 3, k0 = (tid & 7) * 8;
;       float v[8];
; #pragma unroll
;       for (int j = 0; j < 8; ++j) v[j] = tile[(k0 + j) * 65 + n];
;       int no = nb * 64 + n;
;       if (ffn_in_mode) { const int half = no >= DFF ? 1 : 0; const int np = no - half * DFF; no = 256 * (np >> 7) + 128 * half + (np & 127); }
;       u32x4 w; w.x = cvt_pk_bf16(v[0], v[1]); w.y = cvt_pk_bf16(v[2], v[3]); w.z = cvt_pk_bf16(v[4], v[5]); w.w = cvt_pk_bf16(v[6], v[7]);
;       *(u32x4*)(dst + (size_t)no * K + kb * 64 + k0) = w;
;     }
;     __syncthreads();
; DI void convert_layer(LAS unsigned char* lds, const Params& p, int layer) {
;     ...
;     convert_mat(tile, p.ffn_in + (size_t)(layer * 2 + i) * DM * 2 * DFF, DM, 2 * DFF, (bf16_t*)(p.ws + i * SZ_FFN_IN), 1, p.wave_s);
.LBB0_358:
	s_or_b32 s2, s2, 1
	s_and_b64 vcc, exec, s[8:9]
	v_mbcnt_lo_u32_b32 v4, -1, 0
	v_mbcnt_hi_u32_b32 v4, -1, v4
	s_cbranch_vccnz .LBB0_361
	s_add_u32 s8, s86, 0xb00000
	v_readlane_b32 s36, v255, 29
	s_addc_u32 s9, s87, 0
	s_mul_i32 s10, s2, 0x1600000
	v_readlane_b32 s42, v255, 35
	v_readlane_b32 s43, v255, 36
	s_add_u32 s10, s42, s10
	v_lshlrev_b32_e32 v0, 4, v4
	s_addc_u32 s11, s43, 0
	v_or_b32_e32 v3, s79, v4
	v_and_b32_e32 v176, 0xf0, v0
	v_lshlrev_b32_e32 v4, 3, v4
	v_ashrrev_i32_e32 v2, 4, v3
	v_lshl_add_u64 v[0:1], s[10:11], 0, v[176:177]
	v_ashrrev_i32_e32 v3, 3, v3
	v_and_b32_e32 v6, 56, v4
	s_movk_i32 s10, 0x104
	v_add_u32_e32 v5, 0, v176
	v_lshl_add_u32 v7, v3, 2, 0
	v_mul_lo_u32 v4, v2, s10
	s_waitcnt vmcnt(0)
	v_mul_u32_u24_e32 v8, 0x104, v6
	v_add_u32_e32 v4, v5, v4
	v_add_u32_e32 v5, v7, v8
	v_lshlrev_b32_e32 v176, 1, v6
	s_mov_b32 s10, s73
	v_readlane_b32 s37, v255, 30
	v_readlane_b32 s38, v255, 31
	v_readlane_b32 s39, v255, 32
	v_readlane_b32 s40, v255, 33
	v_readlane_b32 s41, v255, 34
	v_readlane_b32 s44, v255, 37
	v_readlane_b32 s45, v255, 38
	v_readlane_b32 s46, v255, 39
	v_readlane_b32 s47, v255, 40
	v_readlane_b32 s48, v255, 41
	v_readlane_b32 s49, v255, 42
	v_readlane_b32 s50, v255, 43
	v_readlane_b32 s51, v255, 44
	s_ashr_i32 s11, s10, 31
	s_lshr_b32 s11, s11, 28
	s_add_i32 s11, s10, s11
	s_and_b32 s12, s11, 0x3fffff0
	s_lshl_b32 s11, s11, 2
	s_sub_i32 s13, s10, s12
	s_and_b32 s12, s11, 0xffffffc0
	s_lshl_b32 s14, s13, 6
	s_ashr_i32 s13, s12, 31
	v_lshl_add_u64 v[34:35], s[12:13], 2, v[0:1]
	v_add_u32_e32 v32, s14, v2
	v_mad_i64_i32 v[30:31], s[16:17], v32, s81, v[34:35]
	v_add_u32_e32 v36, 32, v32
	global_load_dwordx4 v[30:33], v[30:31], off
	v_mad_i64_i32 v[34:35], s[16:17], v36, s81, v[34:35]
	global_load_dwordx4 v[34:37], v[34:35], off
.LBB0_360:
	s_waitcnt vmcnt(0)
	v_mov_b32_e32 v6, v30
	v_mov_b32_e32 v7, v31
	v_mov_b32_e32 v8, v32
	v_mov_b32_e32 v9, v33
	v_mov_b32_e32 v10, v34
	v_mov_b32_e32 v11, v35
	v_mov_b32_e32 v12, v36
	v_mov_b32_e32 v13, v37
	v_add_u32_e32 v14, s12, v3
	v_cmp_lt_i32_e32 vcc, s23, v14
	v_and_b32_e32 v19, 0x7f, v14
	v_add_u32_e32 v16, 0x2080, v4
	v_cndmask_b32_e32 v15, 0, v213, vcc
	v_add_lshl_u32 v14, v15, v14, 1
	v_cndmask_b32_e32 v15, 0, v214, vcc
	v_and_b32_e32 v14, 0xffffff00, v14
	v_or3_b32 v14, v15, v19, v14
	v_add_u32_e32 v17, 0x2088, v4
	v_add_u32_e32 v18, 0x400, v5
	v_ashrrev_i32_e32 v15, 31, v14
	v_lshlrev_b64 v[14:15], 11, v[14:15]
	s_ashr_i32 s15, s14, 31
	v_lshl_add_u64 v[14:15], s[8:9], 0, v[14:15]
	v_lshl_add_u64 v[14:15], s[14:15], 1, v[14:15]
	v_lshl_add_u64 v[14:15], v[14:15], 0, v[176:177]
	s_load_dword s11, s[88:89], 0x10
	s_load_dword s14, s[88:89], 0x0
	s_waitcnt lgkmcnt(0)
	s_lshr_b32 s11, s11, 16
	s_cmp_lg_u32 s11, 0
	s_cselect_b64 s[12:13], -1, 0
	s_cmp_lg_u64 s[12:13], 0
	s_addc_u32 s10, s14, s10
	s_cmpk_lt_i32 s10, 0x580
	s_cselect_b64 s[100:101], -1, 0
	s_cbranch_scc0 .Lcv_skip_360
	s_ashr_i32 s11, s10, 31
	s_lshr_b32 s11, s11, 28
	s_add_i32 s11, s10, s11
	s_and_b32 s12, s11, 0x3fffff0
	s_lshl_b32 s11, s11, 2
	s_sub_i32 s13, s10, s12
	s_and_b32 s12, s11, 0xffffffc0
	s_lshl_b32 s14, s13, 6
	s_ashr_i32 s13, s12, 31
	v_lshl_add_u64 v[34:35], s[12:13], 2, v[0:1]
	v_add_u32_e32 v32, s14, v2
	v_mad_i64_i32 v[30:31], s[16:17], v32, s81, v[34:35]
	v_add_u32_e32 v36, 32, v32
	global_load_dwordx4 v[30:33], v[30:31], off
	v_mad_i64_i32 v[34:35], s[16:17], v36, s81, v[34:35]
	global_load_dwordx4 v[34:37], v[34:35], off

; DI unsigned cvt_pk_bf16(float lo, float hi) { unsigned r; asm volatile("v_cvt_pk_bf16_f32 %0, %1, %2" : "=v"(r) : "v"(lo), "v"(hi)); return r; }
; DI void convert_mat(LAS float* tile, const float* src, int K, int N, bf16_t* dst, int ffn_in_mode, int wave_s) {
;   const int tid = tid_fresh(wave_s), tk = K >> 6, tn = N >> 6;
;   for (int t = blockIdx.x; t < tk * tn; t += gridDim.x) {
;     const int kb = t % tk, nb = t / tk;
; #pragma unroll
;     for (int i = 0; i < 2; ++i) {
;       const int r = (tid >> 4) + 32 * i, c = (tid & 15) * 4;
;       const f32x4 v = *(const f32x4*)(src + (size_t)(kb * 64 + r) * N + nb * 64 + c);
;       tile[r * 65 + c] = v[0]; tile[r * 65 + c + 1] = v[1]; tile[r * 65 + c + 2] = v[2]; tile[r * 65 + c + 3] = v[3];
;     }
;     __syncthreads();
;     {
;       const int n = tid >> 3, k0 = (tid & 7) * 8;
;       float v[8];
; #pragma unroll
;       for (int j = 0; j < 8; ++j) v[j] = tile[(k0 + j) * 65 + n];
;       int no = nb * 64 + n;
;       if (ffn_in_mode) { const int half = no >= DFF ? 1 : 0; const int np = no - half * DFF; no = 256 * (np >> 7) + 128 * half + (np & 127); }
;       u32x4 w; w.x = cvt_pk_bf16(v[0], v[1]); w.y = cvt_pk_bf16(v[2], v[3]); w.z = cvt_pk_bf16(v[4], v[5]); w.w = cvt_pk_bf16(v[6], v[7]);
;       *(u32x4*)(dst + (size_t)no * K + kb * 64 + k0) = w;
;     }
;     __syncthreads();
; DI void convert_layer(LAS unsigned char* lds, const Params& p, int layer) {
;     ...
;     convert_mat(tile, p.ffn_out + (size_t)(layer * 2 + i) * DFF * DM, DFF, DM, (bf16_t*)(p.ws + OFF_FFN_OUT0 + i * SZ_FFN_OUT), 0, p.wave_s);
.LBB0_361:
	s_and_b64 vcc, exec, s[6:7]
	v_mbcnt_lo_u32_b32 v4, -1, 0
	v_mbcnt_hi_u32_b32 v4, -1, v4
	s_cbranch_vccnz .LBB0_364
	s_add_u32 s6, s86, 0x1b80000
	v_readlane_b32 s36, v255, 29
	s_addc_u32 s7, s87, 0
	s_mul_i32 s2, s2, 0xb00000
	v_readlane_b32 s44, v255, 37
	v_or_b32_e32 v3, s79, v4
	v_lshlrev_b32_e32 v0, 4, v4
	v_lshlrev_b32_e32 v4, 3, v4
	v_readlane_b32 s45, v255, 38
	s_add_u32 s8, s44, s2
	v_ashrrev_i32_e32 v2, 4, v3
	v_and_b32_e32 v176, 0xf0, v0
	v_ashrrev_i32_e32 v3, 3, v3
	v_and_b32_e32 v6, 56, v4
	s_movk_i32 s2, 0x104
	s_addc_u32 s9, s45, 0
	v_add_u32_e32 v5, 0, v176
	v_lshl_add_u32 v7, v3, 2, 0
	v_mul_lo_u32 v4, v2, s2
	s_waitcnt vmcnt(0)
	v_mul_u32_u24_e32 v8, 0x104, v6
	v_lshl_add_u64 v[0:1], s[8:9], 0, v[176:177]
	v_add_u32_e32 v4, v5, v4
	v_add_u32_e32 v5, v7, v8
	v_lshlrev_b32_e32 v176, 1, v6
	s_mov_b32 s2, s73
	v_readlane_b32 s37, v255, 30
	v_readlane_b32 s38, v255, 31
	v_readlane_b32 s39, v255, 32
	v_readlane_b32 s40, v255, 33
	v_readlane_b32 s41, v255, 34
	v_readlane_b32 s42, v255, 35
	v_readlane_b32 s43, v255, 36
	v_readlane_b32 s46, v255, 39
	v_readlane_b32 s47, v255, 40
	v_readlane_b32 s48, v255, 41
	v_readlane_b32 s49, v255, 42
	v_readlane_b32 s50, v255, 43
	v_readlane_b32 s51, v255, 44
	s_mul_hi_i32 s8, s2, 0x2e8ba2e9
	s_lshr_b32 s9, s8, 31
	s_ashr_i32 s8, s8, 3
	s_add_i32 s8, s8, s9
	s_mul_i32 s9, s8, 44
	s_sub_i32 s10, s2, s9
	s_lshl_b32 s10, s10, 6
	s_lshl_b32 s8, s8, 6
	v_add_u32_e32 v30, s10, v2
	s_ashr_i32 s9, s8, 31
	v_ashrrev_i32_e32 v31, 31, v30
	v_lshl_add_u64 v[34:35], s[8:9], 2, v[0:1]
	v_add_u32_e32 v32, 32, v30
	v_lshlrev_b64 v[30:31], 12, v[30:31]
	v_ashrrev_i32_e32 v33, 31, v32
	v_lshl_add_u64 v[30:31], v[34:35], 0, v[30:31]
	v_lshlrev_b64 v[36:37], 12, v[32:33]
	global_load_dwordx4 v[30:33], v[30:31], off
	v_lshl_add_u64 v[34:35], v[34:35], 0, v[36:37]
	global_load_dwordx4 v[34:37], v[34:35], off
.LBB0_363:
	s_waitcnt vmcnt(0)
	v_mov_b32_e32 v6, v30
	v_mov_b32_e32 v7, v31
	v_mov_b32_e32 v8, v32
	v_mov_b32_e32 v9, v33
	v_mov_b32_e32 v10, v34
	v_mov_b32_e32 v11, v35
	v_mov_b32_e32 v12, v36
	v_mov_b32_e32 v13, v37
	v_add_u32_e32 v16, 0x2080, v4
	v_add_u32_e32 v17, 0x2088, v4
	v_add_u32_e32 v18, 0x400, v5
	v_mov_b64_e32 v[14:15], s[6:7]
	v_add_u32_e32 v19, s8, v3
	v_mad_i64_i32 v[14:15], s[8:9], v19, s25, v[14:15]
	s_ashr_i32 s11, s10, 31
	v_lshl_add_u64 v[14:15], s[10:11], 1, v[14:15]
	v_lshl_add_u64 v[14:15], v[14:15], 0, v[176:177]
	s_load_dword s8, s[88:89], 0x10
	s_load_dword s10, s[88:89], 0x0
	s_waitcnt lgkmcnt(0)
	s_lshr_b32 s8, s8, 16
	s_cmp_lg_u32 s8, 0
	s_cselect_b64 s[8:9], -1, 0
	s_cmp_lg_u64 s[8:9], 0
	s_addc_u32 s2, s10, s2
	s_cmpk_lt_i32 s2, 0x2c0
	s_cselect_b64 s[100:101], -1, 0
	s_cbranch_scc0 .Lcv_skip_363
	s_mul_hi_i32 s8, s2, 0x2e8ba2e9
	s_lshr_b32 s9, s8, 31
	s_ashr_i32 s8, s8, 3
	s_add_i32 s8, s8, s9
	s_mul_i32 s9, s8, 44
	s_sub_i32 s10, s2, s9
	s_lshl_b32 s10, s10, 6
	s_lshl_b32 s8, s8, 6
	v_add_u32_e32 v30, s10, v2
	s_ashr_i32 s9, s8, 31
	v_ashrrev_i32_e32 v31, 31, v30
	v_lshl_add_u64 v[34:35], s[8:9], 2, v[0:1]
	v_add_u32_e32 v32, 32, v30
	v_lshlrev_b64 v[30:31], 12, v[30:31]
	v_ashrrev_i32_e32 v33, 31, v32
	v_lshl_add_u64 v[30:31], v[34:35], 0, v[30:31]
	v_lshlrev_b64 v[36:37], 12, v[32:33]
	global_load_dwordx4 v[30:33], v[30:31], off
	v_lshl_add_u64 v[34:35], v[34:35], 0, v[36:37]
	global_load_dwordx4 v[34:37], v[34:35], off

; DI unsigned cvt_pk_bf16(float lo, float hi) { unsigned r; asm volatile("v_cvt_pk_bf16_f32 %0, %1, %2" : "=v"(r) : "v"(lo), "v"(hi)); return r; }
; DI void convert_mat(LAS float* tile, const float* src, int K, int N, bf16_t* dst, int ffn_in_mode, int wave_s) {
;   const int tid = tid_fresh(wave_s), tk = K >> 6, tn = N >> 6;
;   for (int t = blockIdx.x; t < tk * tn; t += gridDim.x) {
;     const int kb = t % tk, nb = t / tk;
; #pragma unroll
;     for (int i = 0; i < 2; ++i) {
;       const int r = (tid >> 4) + 32 * i, c = (tid & 15) * 4;
;       const f32x4 v = *(const f32x4*)(src + (size_t)(kb * 64 + r) * N + nb * 64 + c);
;       tile[r * 65 + c] = v[0]; tile[r * 65 + c + 1] = v[1]; tile[r * 65 + c + 2] = v[2]; tile[r * 65 + c + 3] = v[3];
;     }
;     __syncthreads();
;     {
;       const int n = tid >> 3, k0 = (tid & 7) * 8;
;       float v[8];
; #pragma unroll
;       for (int j = 0; j < 8; ++j) v[j] = tile[(k0 + j) * 65 + n];
;       int no = nb * 64 + n;
;       if (ffn_in_mode) { const int half = no >= DFF ? 1 : 0; const int np = no - half * DFF; no = 256 * (np >> 7) + 128 * half + (np & 127); }
;       u32x4 w; w.x = cvt_pk_bf16(v[0], v[1]); w.y = cvt_pk_bf16(v[2], v[3]); w.z = cvt_pk_bf16(v[4], v[5]); w.w = cvt_pk_bf16(v[6], v[7]);
;       *(u32x4*)(dst + (size_t)no * K + kb * 64 + k0) = w;
;     }
;     __syncthreads();
; DI void convert_layer(LAS unsigned char* lds, const Params& p, int layer) {
;     ...
;     convert_mat(tile, p.wret_in, DM, 6144, (bf16_t*)(p.ws + OFF_MIX_IN), 0, p.wave_s);
.LBB0_364:
	s_add_u32 s6, s86, 0x2100000
	s_addc_u32 s7, s87, 0
	s_mov_b64 s[8:9], -1
	s_and_b64 vcc, exec, s[4:5]
	s_cbranch_vccz .LBB0_372
	v_readlane_b32 s4, v254, 48
	v_readlane_b32 s5, v254, 49
	s_andn2_b64 vcc, exec, s[4:5]
	v_mbcnt_lo_u32_b32 v4, -1, 0
	v_mbcnt_hi_u32_b32 v4, -1, v4
	s_cbranch_vccnz .LBB0_368
	v_or_b32_e32 v3, s79, v4
	v_lshlrev_b32_e32 v0, 4, v4
	v_lshlrev_b32_e32 v4, 3, v4
	v_ashrrev_i32_e32 v2, 4, v3
	v_and_b32_e32 v176, 0xf0, v0
	v_ashrrev_i32_e32 v3, 3, v3
	v_and_b32_e32 v6, 56, v4
	s_movk_i32 s2, 0x104
	v_add_u32_e32 v5, 0, v176
	v_lshl_add_u32 v7, v3, 2, 0
	v_mul_lo_u32 v4, v2, s2
	s_waitcnt vmcnt(0)
	v_mul_u32_u24_e32 v8, 0x104, v6
	v_lshl_add_u64 v[0:1], s[60:61], 0, v[176:177]
	v_add_u32_e32 v4, v5, v4
	v_add_u32_e32 v5, v7, v8
	v_lshlrev_b32_e32 v176, 1, v6
	s_mov_b32 s2, s73
	s_ashr_i32 s4, s2, 31
	s_lshr_b32 s4, s4, 28
	s_add_i32 s4, s2, s4
	s_and_b32 s5, s4, 0x3fffff0
	s_lshl_b32 s4, s4, 2
	s_sub_i32 s5, s2, s5
	s_andn2_b32 s4, s4, 63
	s_lshl_b32 s8, s5, 6
	s_ashr_i32 s5, s4, 31
	v_lshl_add_u64 v[34:35], s[4:5], 2, v[0:1]
	v_add_u32_e32 v32, s8, v2
	v_mad_i64_i32 v[30:31], s[10:11], v32, s21, v[34:35]
	v_add_u32_e32 v36, 32, v32
	global_load_dwordx4 v[30:33], v[30:31], off
	v_mad_i64_i32 v[34:35], s[10:11], v36, s21, v[34:35]
	global_load_dwordx4 v[34:37], v[34:35], off
.LBB0_367:
	s_waitcnt vmcnt(0)
	v_mov_b32_e32 v6, v30
	v_mov_b32_e32 v7, v31
	v_mov_b32_e32 v8, v32
	v_mov_b32_e32 v9, v33
	v_mov_b32_e32 v10, v34
	v_mov_b32_e32 v11, v35
	v_mov_b32_e32 v12, v36
	v_mov_b32_e32 v13, v37
	v_add_u32_e32 v14, s4, v3
	v_add_u32_e32 v16, 0x2080, v4
	v_add_u32_e32 v17, 0x2088, v4
	v_add_u32_e32 v18, 0x400, v5
	v_ashrrev_i32_e32 v15, 31, v14
	v_lshlrev_b64 v[14:15], 11, v[14:15]
	s_ashr_i32 s9, s8, 31
	v_lshl_add_u64 v[14:15], s[6:7], 0, v[14:15]
	v_lshl_add_u64 v[14:15], s[8:9], 1, v[14:15]
	v_lshl_add_u64 v[14:15], v[14:15], 0, v[176:177]
	s_load_dword s4, s[88:89], 0x10
	s_load_dword s8, s[88:89], 0x0
	s_waitcnt lgkmcnt(0)
	s_lshr_b32 s4, s4, 16
	s_cmp_lg_u32 s4, 0
	s_cselect_b64 s[4:5], -1, 0
	s_cmp_lg_u64 s[4:5], 0
	s_addc_u32 s2, s8, s2
	s_cmpk_lt_i32 s2, 0x600
	s_cselect_b64 s[100:101], -1, 0
	s_cbranch_scc0 .Lcv_skip_367
	s_ashr_i32 s4, s2, 31
	s_lshr_b32 s4, s4, 28
	s_add_i32 s4, s2, s4
	s_and_b32 s5, s4, 0x3fffff0
	s_lshl_b32 s4, s4, 2
	s_sub_i32 s5, s2, s5
	s_andn2_b32 s4, s4, 63
	s_lshl_b32 s8, s5, 6
	s_ashr_i32 s5, s4, 31
	v_lshl_add_u64 v[34:35], s[4:5], 2, v[0:1]
	v_add_u32_e32 v32, s8, v2
	v_mad_i64_i32 v[30:31], s[10:11], v32, s21, v[34:35]
	v_add_u32_e32 v36, 32, v32
	global_load_dwordx4 v[30:33], v[30:31], off
	v_mad_i64_i32 v[34:35], s[10:11], v36, s21, v[34:35]
	global_load_dwordx4 v[34:37], v[34:35], off

; DI unsigned cvt_pk_bf16(float lo, float hi) { unsigned r; asm volatile("v_cvt_pk_bf16_f32 %0, %1, %2" : "=v"(r) : "v"(lo), "v"(hi)); return r; }
; DI void convert_mat(LAS float* tile, const float* src, int K, int N, bf16_t* dst, int ffn_in_mode, int wave_s) {
;   const int tid = tid_fresh(wave_s), tk = K >> 6, tn = N >> 6;
;   for (int t = blockIdx.x; t < tk * tn; t += gridDim.x) {
;     const int kb = t % tk, nb = t / tk;
; #pragma unroll
;     for (int i = 0; i < 2; ++i) {
;       const int r = (tid >> 4) + 32 * i, c = (tid & 15) * 4;
;       const f32x4 v = *(const f32x4*)(src + (size_t)(kb * 64 + r) * N + nb * 64 + c);
;       tile[r * 65 + c] = v[0]; tile[r * 65 + c + 1] = v[1]; tile[r * 65 + c + 2] = v[2]; tile[r * 65 + c + 3] = v[3];
;     }
;     __syncthreads();
;     {
;       const int n = tid >> 3, k0 = (tid & 7) * 8;
;       float v[8];
; #pragma unroll
;       for (int j = 0; j < 8; ++j) v[j] = tile[(k0 + j) * 65 + n];
;       int no = nb * 64 + n;
;       if (ffn_in_mode) { const int half = no >= DFF ? 1 : 0; const int np = no - half * DFF; no = 256 * (np >> 7) + 128 * half + (np & 127); }
;       u32x4 w; w.x = cvt_pk_bf16(v[0], v[1]); w.y = cvt_pk_bf16(v[2], v[3]); w.z = cvt_pk_bf16(v[4], v[5]); w.w = cvt_pk_bf16(v[6], v[7]);
;       *(u32x4*)(dst + (size_t)no * K + kb * 64 + k0) = w;
;     }
;     __syncthreads();
; DI void convert_layer(LAS unsigned char* lds, const Params& p, int layer) {
;     ...
;     convert_mat(tile, p.wret_o, 2048, DM, (bf16_t*)(p.ws + OFF_MIX_OUT), 0, p.wave_s);
.LBB0_368:
	v_readlane_b32 s4, v254, 2
	v_readlane_b32 s5, v254, 3
	s_andn2_b64 vcc, exec, s[4:5]
	v_mbcnt_lo_u32_b32 v4, -1, 0
	v_mbcnt_hi_u32_b32 v4, -1, v4
	s_cbranch_vccnz .LBB0_371
	v_or_b32_e32 v3, s79, v4
	v_lshlrev_b32_e32 v0, 4, v4
	v_lshlrev_b32_e32 v4, 3, v4
	v_ashrrev_i32_e32 v2, 4, v3
	v_and_b32_e32 v176, 0xf0, v0
	v_ashrrev_i32_e32 v3, 3, v3
	v_and_b32_e32 v6, 56, v4
	s_movk_i32 s2, 0x104
	s_add_u32 s4, s86, 0x2d00000
	v_add_u32_e32 v5, 0, v176
	v_lshl_add_u32 v7, v3, 2, 0
	v_mul_lo_u32 v4, v2, s2
	s_waitcnt vmcnt(0)
	v_mul_u32_u24_e32 v8, 0x104, v6
	s_addc_u32 s5, s87, 0
	v_lshl_add_u64 v[0:1], s[62:63], 0, v[176:177]
	v_add_u32_e32 v4, v5, v4
	v_add_u32_e32 v5, v7, v8
	v_lshlrev_b32_e32 v176, 1, v6
	s_mov_b32 s2, s73
	s_ashr_i32 s8, s2, 31
	s_lshr_b32 s8, s8, 27
	s_add_i32 s8, s2, s8
	s_and_b32 s9, s8, 0x3ffffe0
	s_sub_i32 s9, s2, s9
	s_lshl_b32 s8, s8, 1
	s_lshl_b32 s10, s9, 6
	s_andn2_b32 s8, s8, 63
	v_add_u32_e32 v30, s10, v2
	s_ashr_i32 s9, s8, 31
	v_ashrrev_i32_e32 v31, 31, v30
	v_lshl_add_u64 v[34:35], s[8:9], 2, v[0:1]
	v_add_u32_e32 v32, 32, v30
	v_lshlrev_b64 v[30:31], 12, v[30:31]
	v_ashrrev_i32_e32 v33, 31, v32
	v_lshl_add_u64 v[30:31], v[34:35], 0, v[30:31]
	v_lshlrev_b64 v[36:37], 12, v[32:33]
	global_load_dwordx4 v[30:33], v[30:31], off
	v_lshl_add_u64 v[34:35], v[34:35], 0, v[36:37]
	global_load_dwordx4 v[34:37], v[34:35], off
.LBB0_370:
	s_waitcnt vmcnt(0)
	v_mov_b32_e32 v6, v30
	v_mov_b32_e32 v7, v31
	v_mov_b32_e32 v8, v32
	v_mov_b32_e32 v9, v33
	v_mov_b32_e32 v10, v34
	v_mov_b32_e32 v11, v35
	v_mov_b32_e32 v12, v36
	v_mov_b32_e32 v13, v37
	v_add_u32_e32 v14, s8, v3
	v_add_u32_e32 v16, 0x2080, v4
	v_add_u32_e32 v17, 0x2088, v4
	v_add_u32_e32 v18, 0x400, v5
	v_ashrrev_i32_e32 v15, 31, v14
	v_lshlrev_b64 v[14:15], 12, v[14:15]
	s_ashr_i32 s11, s10, 31
	v_lshl_add_u64 v[14:15], s[4:5], 0, v[14:15]
	v_lshl_add_u64 v[14:15], s[10:11], 1, v[14:15]
	v_lshl_add_u64 v[14:15], v[14:15], 0, v[176:177]
	s_load_dword s8, s[88:89], 0x10
	s_load_dword s10, s[88:89], 0x0
	s_waitcnt lgkmcnt(0)
	s_lshr_b32 s8, s8, 16
	s_cmp_lg_u32 s8, 0
	s_cselect_b64 s[8:9], -1, 0
	s_cmp_lg_u64 s[8:9], 0
	s_addc_u32 s2, s10, s2
	s_cmpk_lt_i32 s2, 0x200
	s_cselect_b64 s[100:101], -1, 0
	s_cbranch_scc0 .Lcv_skip_370
	s_ashr_i32 s8, s2, 31
	s_lshr_b32 s8, s8, 27
	s_add_i32 s8, s2, s8
	s_and_b32 s9, s8, 0x3ffffe0
	s_sub_i32 s9, s2, s9
	s_lshl_b32 s8, s8, 1
	s_lshl_b32 s10, s9, 6
	s_andn2_b32 s8, s8, 63
	v_add_u32_e32 v30, s10, v2
	s_ashr_i32 s9, s8, 31
	v_ashrrev_i32_e32 v31, 31, v30
	v_lshl_add_u64 v[34:35], s[8:9], 2, v[0:1]
	v_add_u32_e32 v32, 32, v30
	v_lshlrev_b64 v[30:31], 12, v[30:31]
	v_ashrrev_i32_e32 v33, 31, v32
	v_lshl_add_u64 v[30:31], v[34:35], 0, v[30:31]
	v_lshlrev_b64 v[36:37], 12, v[32:33]
	global_load_dwordx4 v[30:33], v[30:31], off
	v_lshl_add_u64 v[34:35], v[34:35], 0, v[36:37]
	global_load_dwordx4 v[34:37], v[34:35], off

; DI unsigned cvt_pk_bf16(float lo, float hi) { unsigned r; asm volatile("v_cvt_pk_bf16_f32 %0, %1, %2" : "=v"(r) : "v"(lo), "v"(hi)); return r; }
; DI void convert_mat(LAS float* tile, const float* src, int K, int N, bf16_t* dst, int ffn_in_mode, int wave_s) {
;   const int tid = tid_fresh(wave_s), tk = K >> 6, tn = N >> 6;
;   for (int t = blockIdx.x; t < tk * tn; t += gridDim.x) {
;     const int kb = t % tk, nb = t / tk;
; #pragma unroll
;     for (int i = 0; i < 2; ++i) {
;       const int r = (tid >> 4) + 32 * i, c = (tid & 15) * 4;
;       const f32x4 v = *(const f32x4*)(src + (size_t)(kb * 64 + r) * N + nb * 64 + c);
;       tile[r * 65 + c] = v[0]; tile[r * 65 + c + 1] = v[1]; tile[r * 65 + c + 2] = v[2]; tile[r * 65 + c + 3] = v[3];
;     }
;     __syncthreads();
;     {
;       const int n = tid >> 3, k0 = (tid & 7) * 8;
;       float v[8];
; #pragma unroll
;       for (int j = 0; j < 8; ++j) v[j] = tile[(k0 + j) * 65 + n];
;       int no = nb * 64 + n;
;       if (ffn_in_mode) { const int half = no >= DFF ? 1 : 0; const int np = no - half * DFF; no = 256 * (np >> 7) + 128 * half + (np & 127); }
;       u32x4 w; w.x = cvt_pk_bf16(v[0], v[1]); w.y = cvt_pk_bf16(v[2], v[3]); w.z = cvt_pk_bf16(v[4], v[5]); w.w = cvt_pk_bf16(v[6], v[7]);
;       *(u32x4*)(dst + (size_t)no * K + kb * 64 + k0) = w;
;     }
;     __syncthreads();
; DI void convert_layer(LAS unsigned char* lds, const Params& p, int layer) {
;     ...
;     convert_mat(tile, p.wqkv, DM, 1536, (bf16_t*)(p.ws + OFF_MIX_IN), 0, p.wave_s);
.LBB0_372:
	s_and_b64 vcc, exec, s[8:9]
	s_cbranch_vccz .LBB0_379
	v_readlane_b32 s4, v254, 50
	v_readlane_b32 s5, v254, 51
	s_andn2_b64 vcc, exec, s[4:5]
	v_mbcnt_lo_u32_b32 v4, -1, 0
	v_mbcnt_hi_u32_b32 v4, -1, v4
	s_cbranch_vccnz .LBB0_376
	v_or_b32_e32 v3, s79, v4
	v_lshlrev_b32_e32 v0, 4, v4
	v_lshlrev_b32_e32 v4, 3, v4
	v_ashrrev_i32_e32 v2, 4, v3
	v_and_b32_e32 v176, 0xf0, v0
	v_readlane_b32 s36, v255, 29
	v_ashrrev_i32_e32 v3, 3, v3
	v_and_b32_e32 v6, 56, v4
	s_movk_i32 s2, 0x104
	v_readlane_b32 s46, v255, 39
	v_readlane_b32 s47, v255, 40
	v_add_u32_e32 v5, 0, v176
	v_lshl_add_u32 v7, v3, 2, 0
	v_mul_lo_u32 v4, v2, s2
	s_waitcnt vmcnt(0)
	v_mul_u32_u24_e32 v8, 0x104, v6
	v_lshl_add_u64 v[0:1], s[46:47], 0, v[176:177]
	v_add_u32_e32 v4, v5, v4
	v_add_u32_e32 v5, v7, v8
	v_lshlrev_b32_e32 v176, 1, v6
	s_mov_b32 s2, s73
	v_readlane_b32 s37, v255, 30
	v_readlane_b32 s38, v255, 31
	v_readlane_b32 s39, v255, 32
	v_readlane_b32 s40, v255, 33
	v_readlane_b32 s41, v255, 34
	v_readlane_b32 s42, v255, 35
	v_readlane_b32 s43, v255, 36
	v_readlane_b32 s44, v255, 37
	v_readlane_b32 s45, v255, 38
	v_readlane_b32 s48, v255, 41
	v_readlane_b32 s49, v255, 42
	v_readlane_b32 s50, v255, 43
	v_readlane_b32 s51, v255, 44
	s_ashr_i32 s4, s2, 31
	s_lshr_b32 s4, s4, 28
	s_add_i32 s4, s2, s4
	s_and_b32 s5, s4, 0x3fffff0
	s_lshl_b32 s4, s4, 2
	s_sub_i32 s5, s2, s5
	s_andn2_b32 s4, s4, 63
	s_lshl_b32 s8, s5, 6
	s_ashr_i32 s5, s4, 31
	v_lshl_add_u64 v[34:35], s[4:5], 2, v[0:1]
	v_add_u32_e32 v32, s8, v2
	v_mad_i64_i32 v[30:31], s[10:11], v32, s20, v[34:35]
	v_add_u32_e32 v36, 32, v32
	global_load_dwordx4 v[30:33], v[30:31], off
	v_mad_i64_i32 v[34:35], s[10:11], v36, s20, v[34:35]
	global_load_dwordx4 v[34:37], v[34:35], off
.LBB0_375:
	s_waitcnt vmcnt(0)
	v_mov_b32_e32 v6, v30
	v_mov_b32_e32 v7, v31
	v_mov_b32_e32 v8, v32
	v_mov_b32_e32 v9, v33
	v_mov_b32_e32 v10, v34
	v_mov_b32_e32 v11, v35
	v_mov_b32_e32 v12, v36
	v_mov_b32_e32 v13, v37
	v_add_u32_e32 v14, s4, v3
	v_add_u32_e32 v16, 0x2080, v4
	v_add_u32_e32 v17, 0x2088, v4
	v_add_u32_e32 v18, 0x400, v5
	v_ashrrev_i32_e32 v15, 31, v14
	v_lshlrev_b64 v[14:15], 11, v[14:15]
	s_ashr_i32 s9, s8, 31
	v_lshl_add_u64 v[14:15], s[6:7], 0, v[14:15]
	v_lshl_add_u64 v[14:15], s[8:9], 1, v[14:15]
	v_lshl_add_u64 v[14:15], v[14:15], 0, v[176:177]
	s_load_dword s4, s[88:89], 0x10
	s_load_dword s8, s[88:89], 0x0
	s_waitcnt lgkmcnt(0)
	s_lshr_b32 s4, s4, 16
	s_cmp_lg_u32 s4, 0
	s_cselect_b64 s[4:5], -1, 0
	s_cmp_lg_u64 s[4:5], 0
	s_addc_u32 s2, s8, s2
	s_cmpk_lt_i32 s2, 0x180
	s_cselect_b64 s[100:101], -1, 0
	s_cbranch_scc0 .Lcv_skip_375
	s_ashr_i32 s4, s2, 31
	s_lshr_b32 s4, s4, 28
	s_add_i32 s4, s2, s4
	s_and_b32 s5, s4, 0x3fffff0
	s_lshl_b32 s4, s4, 2
	s_sub_i32 s5, s2, s5
	s_andn2_b32 s4, s4, 63
	s_lshl_b32 s8, s5, 6
	s_ashr_i32 s5, s4, 31
	v_lshl_add_u64 v[34:35], s[4:5], 2, v[0:1]
	v_add_u32_e32 v32, s8, v2
	v_mad_i64_i32 v[30:31], s[10:11], v32, s20, v[34:35]
	v_add_u32_e32 v36, 32, v32
	global_load_dwordx4 v[30:33], v[30:31], off
	v_mad_i64_i32 v[34:35], s[10:11], v36, s20, v[34:35]
	global_load_dwordx4 v[34:37], v[34:35], off

; DI unsigned cvt_pk_bf16(float lo, float hi) { unsigned r; asm volatile("v_cvt_pk_bf16_f32 %0, %1, %2" : "=v"(r) : "v"(lo), "v"(hi)); return r; }
; DI void convert_mat(LAS float* tile, const float* src, int K, int N, bf16_t* dst, int ffn_in_mode, int wave_s) {
;   const int tid = tid_fresh(wave_s), tk = K >> 6, tn = N >> 6;
;   for (int t = blockIdx.x; t < tk * tn; t += gridDim.x) {
;     const int kb = t % tk, nb = t / tk;
; #pragma unroll
;     for (int i = 0; i < 2; ++i) {
;       const int r = (tid >> 4) + 32 * i, c = (tid & 15) * 4;
;       const f32x4 v = *(const f32x4*)(src + (size_t)(kb * 64 + r) * N + nb * 64 + c);
;       tile[r * 65 + c] = v[0]; tile[r * 65 + c + 1] = v[1]; tile[r * 65 + c + 2] = v[2]; tile[r * 65 + c + 3] = v[3];
;     }
;     __syncthreads();
;     {
;       const int n = tid >> 3, k0 = (tid & 7) * 8;
;       float v[8];
; #pragma unroll
;       for (int j = 0; j < 8; ++j) v[j] = tile[(k0 + j) * 65 + n];
;       int no = nb * 64 + n;
;       if (ffn_in_mode) { const int half = no >= DFF ? 1 : 0; const int np = no - half * DFF; no = 256 * (np >> 7) + 128 * half + (np & 127); }
;       u32x4 w; w.x = cvt_pk_bf16(v[0], v[1]); w.y = cvt_pk_bf16(v[2], v[3]); w.z = cvt_pk_bf16(v[4], v[5]); w.w = cvt_pk_bf16(v[6], v[7]);
;       *(u32x4*)(dst + (size_t)no * K + kb * 64 + k0) = w;
;     }
;     __syncthreads();
; DI void convert_layer(LAS unsigned char* lds, const Params& p, int layer) {
;     ...
;     convert_mat(tile, p.wao, DM, DM, (bf16_t*)(p.ws + OFF_MIX_OUT), 0, p.wave_s);
.LBB0_376:
	v_readlane_b32 s4, v254, 6
	v_readlane_b32 s5, v254, 7
	s_andn2_b64 vcc, exec, s[4:5]
	v_mbcnt_lo_u32_b32 v4, -1, 0
	v_mbcnt_hi_u32_b32 v4, -1, v4
	s_cbranch_vccnz .LBB0_379
	v_or_b32_e32 v3, s79, v4
	v_lshlrev_b32_e32 v0, 4, v4
	v_lshlrev_b32_e32 v4, 3, v4
	v_ashrrev_i32_e32 v2, 4, v3
	v_and_b32_e32 v176, 0xf0, v0
	v_readlane_b32 s36, v255, 29
	v_ashrrev_i32_e32 v3, 3, v3
	v_and_b32_e32 v6, 56, v4
	s_movk_i32 s2, 0x104
	s_add_u32 s4, s86, 0x2d00000
	v_readlane_b32 s48, v255, 41
	v_readlane_b32 s49, v255, 42
	v_add_u32_e32 v5, 0, v176
	v_lshl_add_u32 v7, v3, 2, 0
	v_mul_lo_u32 v4, v2, s2
	s_waitcnt vmcnt(0)
	v_mul_u32_u24_e32 v8, 0x104, v6
	s_addc_u32 s5, s87, 0
	v_lshl_add_u64 v[0:1], s[48:49], 0, v[176:177]
	v_add_u32_e32 v4, v5, v4
	v_add_u32_e32 v5, v7, v8
	v_lshlrev_b32_e32 v176, 1, v6
	s_mov_b32 s2, s73
	v_readlane_b32 s37, v255, 30
	v_readlane_b32 s38, v255, 31
	v_readlane_b32 s39, v255, 32
	v_readlane_b32 s40, v255, 33
	v_readlane_b32 s41, v255, 34
	v_readlane_b32 s42, v255, 35
	v_readlane_b32 s43, v255, 36
	v_readlane_b32 s44, v255, 37
	v_readlane_b32 s45, v255, 38
	v_readlane_b32 s46, v255, 39
	v_readlane_b32 s47, v255, 40
	v_readlane_b32 s50, v255, 43
	v_readlane_b32 s51, v255, 44
	s_ashr_i32 s6, s2, 31
	s_lshr_b32 s6, s6, 28
	s_add_i32 s6, s2, s6
	s_and_b32 s7, s6, 0x3fffff0
	s_sub_i32 s7, s2, s7
	s_lshl_b32 s6, s6, 2
	s_lshl_b32 s8, s7, 6
	s_andn2_b32 s6, s6, 63
	v_add_u32_e32 v30, s8, v2
	s_ashr_i32 s7, s6, 31
	v_ashrrev_i32_e32 v31, 31, v30
	v_lshl_add_u64 v[34:35], s[6:7], 2, v[0:1]
	v_add_u32_e32 v32, 32, v30
	v_lshlrev_b64 v[30:31], 12, v[30:31]
	v_ashrrev_i32_e32 v33, 31, v32
	v_lshl_add_u64 v[30:31], v[34:35], 0, v[30:31]
	v_lshlrev_b64 v[36:37], 12, v[32:33]
	global_load_dwordx4 v[30:33], v[30:31], off
	v_lshl_add_u64 v[34:35], v[34:35], 0, v[36:37]
	global_load_dwordx4 v[34:37], v[34:35], off
.LBB0_378:
	s_waitcnt vmcnt(0)
	v_mov_b32_e32 v6, v30
	v_mov_b32_e32 v7, v31
	v_mov_b32_e32 v8, v32
	v_mov_b32_e32 v9, v33
	v_mov_b32_e32 v10, v34
	v_mov_b32_e32 v11, v35
	v_mov_b32_e32 v12, v36
	v_mov_b32_e32 v13, v37
	v_add_u32_e32 v14, s6, v3
	v_add_u32_e32 v16, 0x2080, v4
	v_add_u32_e32 v17, 0x2088, v4
	v_add_u32_e32 v18, 0x400, v5
	v_ashrrev_i32_e32 v15, 31, v14
	v_lshlrev_b64 v[14:15], 11, v[14:15]
	s_ashr_i32 s9, s8, 31
	v_lshl_add_u64 v[14:15], s[4:5], 0, v[14:15]
	v_lshl_add_u64 v[14:15], s[8:9], 1, v[14:15]
	v_lshl_add_u64 v[14:15], v[14:15], 0, v[176:177]
	s_load_dword s6, s[88:89], 0x10
	s_load_dword s8, s[88:89], 0x0
	s_waitcnt lgkmcnt(0)
	s_lshr_b32 s6, s6, 16
	s_cmp_lg_u32 s6, 0
	s_cselect_b64 s[6:7], -1, 0
	s_cmp_lg_u64 s[6:7], 0
	s_addc_u32 s2, s8, s2
	s_cmpk_gt_i32 s2, 0xff
	s_cselect_b64 s[100:101], 0, -1
	s_cbranch_scc1 .Lcv_skip_378
	s_ashr_i32 s6, s2, 31
	s_lshr_b32 s6, s6, 28
	s_add_i32 s6, s2, s6
	s_and_b32 s7, s6, 0x3fffff0
	s_sub_i32 s7, s2, s7
	s_lshl_b32 s6, s6, 2
	s_lshl_b32 s8, s7, 6
	s_andn2_b32 s6, s6, 63
	v_add_u32_e32 v30, s8, v2
	s_ashr_i32 s7, s6, 31
	v_ashrrev_i32_e32 v31, 31, v30
	v_lshl_add_u64 v[34:35], s[6:7], 2, v[0:1]
	v_add_u32_e32 v32, 32, v30
	v_lshlrev_b64 v[30:31], 12, v[30:31]
	v_ashrrev_i32_e32 v33, 31, v32
	v_lshl_add_u64 v[30:31], v[34:35], 0, v[30:31]
	v_lshlrev_b64 v[36:37], 12, v[32:33]
	global_load_dwordx4 v[30:33], v[30:31], off
	v_lshl_add_u64 v[34:35], v[34:35], 0, v[36:37]
	global_load_dwordx4 v[34:37], v[34:35], off

; #define LAS __attribute__((address_space(3)))
; __global__ void __launch_bounds__(512, 2) fwd_megakernel(Params pin) {
;   extern __shared__ __attribute__((aligned(16))) unsigned char shm[];
;   LAS unsigned char* lds = (LAS unsigned char*)shm;
;   const int wave_s = __builtin_amdgcn_readfirstlane((int)(threadIdx.x >> 6));
	.amdhsa_kernel _Z14fwd_megakernel6Params
		.amdhsa_group_segment_fixed_size 0
		.amdhsa_private_segment_fixed_size 0
		.amdhsa_kernarg_size 384
		.amdhsa_user_sgpr_count 2
		.amdhsa_user_sgpr_dispatch_ptr 0
		.amdhsa_user_sgpr_queue_ptr 0
		.amdhsa_user_sgpr_kernarg_segment_ptr 1
		.amdhsa_user_sgpr_dispatch_id 0
		.amdhsa_user_sgpr_kernarg_preload_length 0
		.amdhsa_user_sgpr_kernarg_preload_offset 0
		.amdhsa_user_sgpr_private_segment_size 0
		.amdhsa_uses_dynamic_stack 0
		.amdhsa_enable_private_segment 0
		.amdhsa_system_sgpr_workgroup_id_x 1
		.amdhsa_system_sgpr_workgroup_id_y 0
		.amdhsa_system_sgpr_workgroup_id_z 0
		.amdhsa_system_sgpr_workgroup_info 0
		.amdhsa_system_vgpr_workitem_id 2
		.amdhsa_next_free_vgpr 256
		.amdhsa_next_free_sgpr 102
		.amdhsa_accum_offset 256
		.amdhsa_reserve_vcc 1
		.amdhsa_float_round_mode_32 0
		.amdhsa_float_round_mode_16_64 0
		.amdhsa_float_denorm_mode_32 3
		.amdhsa_float_denorm_mode_16_64 3
		.amdhsa_dx10_clamp 1
		.amdhsa_ieee_mode 1
		.amdhsa_fp16_overflow 0
		.amdhsa_tg_split 0
		.amdhsa_exception_fp_ieee_invalid_op 0
		.amdhsa_exception_fp_denorm_src 0
		.amdhsa_exception_fp_ieee_div_zero 0
		.amdhsa_exception_fp_ieee_overflow 0
		.amdhsa_exception_fp_ieee_underflow 0
		.amdhsa_exception_fp_ieee_inexact 0
		.amdhsa_exception_int_div_zero 0
	.end_amdhsa_kernel

; #define LAS __attribute__((address_space(3)))
; __global__ void __launch_bounds__(512, 2) fwd_megakernel(Params pin) {
;   extern __shared__ __attribute__((aligned(16))) unsigned char shm[];
;   LAS unsigned char* lds = (LAS unsigned char*)shm;
;   const int wave_s = __builtin_amdgcn_readfirstlane((int)(threadIdx.x >> 6));
amdhsa.kernels:
  - .agpr_count:     0
    .args:
      - .offset:         0
        .size:           128
        .value_kind:     by_value
      - .offset:         128
        .size:           4
        .value_kind:     hidden_block_count_x
      - .offset:         132
        .size:           4
        .value_kind:     hidden_block_count_y
      - .offset:         136
        .size:           4
        .value_kind:     hidden_block_count_z
      - .offset:         140
        .size:           2
        .value_kind:     hidden_group_size_x
      - .offset:         142
        .size:           2
        .value_kind:     hidden_group_size_y
      - .offset:         144
        .size:           2
        .value_kind:     hidden_group_size_z
      - .offset:         146
        .size:           2
        .value_kind:     hidden_remainder_x
      - .offset:         148
        .size:           2
        .value_kind:     hidden_remainder_y
      - .offset:         150
        .size:           2
        .value_kind:     hidden_remainder_z
      - .offset:         168
        .size:           8
        .value_kind:     hidden_global_offset_x
      - .offset:         176
        .size:           8
        .value_kind:     hidden_global_offset_y
      - .offset:         184
        .size:           8
        .value_kind:     hidden_global_offset_z
      - .offset:         192
        .size:           2
        .value_kind:     hidden_grid_dims
      - .offset:         216
        .size:           8
        .value_kind:     hidden_multigrid_sync_arg
      - .offset:         248
        .size:           4
        .value_kind:     hidden_dynamic_lds_size
    .group_segment_fixed_size: 0
    .kernarg_segment_align: 8
    .kernarg_segment_size: 384
    .language:       OpenCL C
    .language_version:
      - 2
      - 0
    .max_flat_workgroup_size: 512
    .name:           _Z14fwd_megakernel6Params
    .private_segment_fixed_size: 0
    .sgpr_count:     108
    .sgpr_spill_count: 144
    .symbol:         _Z14fwd_megakernel6Params.kd
    .uniform_work_group_size: 1
    .uses_dynamic_stack: false
    .vgpr_count:     256
    .vgpr_spill_count: 0
    .wavefront_size: 64
